# mixer B: the 16 score scalings v_mul_f32 -> 8 v_pk_mul_f32 (same products, VALU-bound loop)
# baseline (speedup 1.0000x reference)
; DI size_t zrowU(int row0, int NT) { return ((size_t)((row0 >> 8) * NT) << 16) + (size_t)((((row0 >> 7) & 1) << 15) | (((row0 >> 5) & 1) << 14) | (((row0 >> 6) & 1) << 11)); }
; #define MFMA32(a, b, c) __builtin_amdgcn_mfma_f32_32x32x16_bf16((a), (b), (c), 0, 0, 0)
; template <bool MASKED>
; DI void attnB_tile_math(const f32x16& S, int kpos0, int kvalid, int qpos, int h, int lane, float& later, unsigned (&pw)[8]) {
;     const float scale2 = 0.08838834764831845f * 1.4426950408889634f;
;     float x2[16], sp[16];
; #pragma unroll
;     for (int r = 0; r < 16; ++r) {
;         const float x = S[r] * scale2; x2[r] = x;
; DI void attnB_item(bf16_t* z, int hh, int qs, LAS bf16_t* vs, int lane) {
;     ...
;         const int kpos0 = t < 0 ? 0 : NMETA + 32 * t, kvalid = t < 0 ? NMETA : 32;
;         const int tn = t <= 0 ? -1 : t - 1;
;         const size_t ron = zrowU(tn < 0 ? SEQ : 32 * tn, 32);
;         f32x16 S; bf16x8 qf[8];
; #pragma unroll
;         for (int i = 0; i < 16; ++i) S[i] = 0.f;
; #pragma unroll
;         for (int s = 0; s < 8; ++s) qf[s] = qs_lds[64 * s];
;         asm volatile("s_waitcnt lgkmcnt(0)" ::: "memory"); __builtin_amdgcn_sched_barrier(0);
;         __builtin_amdgcn_s_setprio(1);
; #pragma unroll
;         for (int s = 0; s < 8; ++s) S = MFMA32(kf[s], qf[s], S);
;         __builtin_amdgcn_s_setprio(0);
; #pragma unroll
;         for (int s = 0; s < 8; ++s) kf[s] = *(const bf16x8*)(kbase + ron + (((s >> 1) << 9) | ((s & 1) << 8)));
.LBB0_151:
	s_waitcnt vmcnt(8)
	v_mov_b64_e32 v[148:149], v[144:145]
	v_mov_b64_e32 v[146:147], v[142:143]
	s_cmp_lt_i32 s30, 0
	ds_read_b128 v[66:69], v182 offset:10240
	ds_read_b128 v[142:145], v182 offset:11264
	ds_read_b128 v[150:153], v182 offset:12288
	ds_read_b128 v[192:195], v182 offset:13312
	ds_read_b128 v[196:199], v182 offset:14336
	ds_read_b128 v[200:203], v182 offset:15360
	ds_read_b128 v[204:207], v182 offset:16384
	ds_read_b128 v[208:211], v182 offset:17408
	s_cselect_b64 s[8:9], -1, 0
	s_cmp_gt_i32 s30, -1
	s_cselect_b64 s[4:5], -1, 0
	s_max_i32 s29, s30, 0
	s_add_i32 s29, s29, -1
	s_lshl_b32 s6, s29, 5
	s_cmp_gt_i32 s30, 0
	s_cselect_b32 s10, s6, 0x4000
	s_ashr_i32 s6, s10, 3
	s_lshl_b32 s11, s10, 8
	s_lshl_b32 s31, s10, 9
	s_andn2_b32 s6, s6, 31
	s_and_b32 s11, s11, 0x8000
	s_and_b32 s31, s31, 0x4000
	s_lshl_b32 s10, s10, 5
	s_waitcnt lgkmcnt(0)
	s_ashr_i32 s7, s6, 31
	s_or_b32 s11, s11, s31
	s_and_b32 s10, s10, 0x800
	s_or_b32 s10, s11, s10
	s_lshl_b64 s[6:7], s[6:7], 16
	s_setprio 1
	s_or_b32 s6, s6, s10
	s_waitcnt lgkmcnt(7)
	v_mfma_f32_32x32x16_bf16 v[66:81], v[114:117], v[66:69], 0
	s_cmp_lg_u32 s30, s28
	s_cselect_b64 s[10:11], -1, 0
	s_and_b64 s[38:39], s[10:11], s[4:5]
	s_mov_b64 s[10:11], -1
	v_add_f32_e32 v191, 0, v189
	s_and_b64 vcc, exec, s[38:39]
	s_waitcnt lgkmcnt(6)
	v_mfma_f32_32x32x16_bf16 v[66:81], v[118:121], v[142:145], v[66:81]
	v_lshl_add_u64 v[142:143], s[6:7], 1, v[158:159]
	s_waitcnt lgkmcnt(5)
	v_mfma_f32_32x32x16_bf16 v[66:81], v[122:125], v[150:153], v[66:81]
	s_waitcnt lgkmcnt(4)
	v_mfma_f32_32x32x16_bf16 v[66:81], v[126:129], v[192:195], v[66:81]
	s_waitcnt lgkmcnt(3)
	v_mfma_f32_32x32x16_bf16 v[66:81], v[130:133], v[196:199], v[66:81]
	s_waitcnt lgkmcnt(2)
	v_mfma_f32_32x32x16_bf16 v[66:81], v[134:137], v[200:203], v[66:81]
	global_load_dwordx4 v[114:117], v[142:143], off
	global_load_dwordx4 v[118:121], v[142:143], off offset:512
	global_load_dwordx4 v[122:125], v[142:143], off offset:1024
	global_load_dwordx4 v[126:129], v[142:143], off offset:1536
	global_load_dwordx4 v[130:133], v[142:143], off offset:2048
	global_load_dwordx4 v[134:137], v[142:143], off offset:2560
	s_waitcnt lgkmcnt(1)
	v_mfma_f32_32x32x16_bf16 v[66:81], v[138:141], v[204:207], v[66:81]
	global_load_dwordx4 v[138:141], v[142:143], off offset:3072
	s_nop 0
	global_load_dwordx4 v[142:145], v[142:143], off offset:3584
	s_waitcnt lgkmcnt(0)
	v_mfma_f32_32x32x16_bf16 v[66:81], v[146:149], v[208:211], v[66:81]
	s_setprio 0
	s_nop 11
	v_pk_mul_f32 v[206:207], v[66:67], s[16:17] op_sel:[1,0] op_sel_hi:[0,0]
	v_pk_mul_f32 v[204:205], v[68:69], s[16:17] op_sel:[1,0] op_sel_hi:[0,0]
	v_pk_mul_f32 v[202:203], v[70:71], s[16:17] op_sel:[1,0] op_sel_hi:[0,0]
	v_pk_mul_f32 v[200:201], v[72:73], s[16:17] op_sel:[1,0] op_sel_hi:[0,0]
	v_pk_mul_f32 v[198:199], v[74:75], s[16:17] op_sel:[1,0] op_sel_hi:[0,0]
	v_pk_mul_f32 v[196:197], v[76:77], s[16:17] op_sel:[1,0] op_sel_hi:[0,0]
	v_pk_mul_f32 v[194:195], v[78:79], s[16:17] op_sel:[1,0] op_sel_hi:[0,0]
	v_pk_mul_f32 v[192:193], v[80:81], s[16:17] op_sel:[1,0] op_sel_hi:[0,0]
	s_cbranch_vccz .LBB0_153
; DI unsigned pk2(float a, float b) { f32x2 v = {a, b}; bf16v2 r = __builtin_convertvector(v, bf16v2); return __builtin_bit_cast(unsigned, r); }
; DI float shflx(float v, int mask, int lane) { return __int_as_float(__builtin_amdgcn_ds_bpermute((lane ^ mask) << 2, __float_as_int(v))); }
; template <bool MASKED>
; DI void attnB_tile_math(const f32x16& S, int kpos0, int kvalid, int qpos, int h, int lane, float& later, unsigned (&pw)[8]) {
;     ...
;     for (int r = 0; r < 16; ++r) {
;         const float x = S[r] * scale2; x2[r] = x;
;         const float e = __builtin_amdgcn_exp2f(-fabsf(x));
;         const float v = fmaxf(x, 0.f) + __builtin_amdgcn_logf(1.0f + e);
;         if (MASKED) { const int row = (r & 3) + 8 * (r >> 2) + 4 * h; const bool vis = (row < kvalid) && (kpos0 + row < qpos); sp[r] = vis ? v : 0.f; }
;         else sp[r] = v;
;     }
;     float G[4], P[4];
; #pragma unroll
;     for (int g = 0; g < 4; ++g) { G[g] = (sp[4 * g] + sp[4 * g + 1]) + (sp[4 * g + 2] + sp[4 * g + 3]); P[g] = shflx(G[g], 32, lane); }
;     float R[4]; R[3] = 0.f; R[2] = G[3] + P[3]; R[1] = R[2] + (G[2] + P[2]); R[0] = R[1] + (G[1] + P[1]);
;     const float total = R[0] + (G[0] + P[0]);
; #pragma unroll
;     for (int g = 0; g < 4; ++g) {
;         float sfx = later + R[g] + (h == 0 ? P[g] : 0.f); float wv[4];
; #pragma unroll
;         for (int i = 3; i >= 0; --i) {
;             const int r = 4 * g + i;
;             sfx += sp[r];
;             float t = __builtin_amdgcn_exp2f(x2[r] - sfx);
;             if (MASKED) { const int row = (r & 3) + 8 * (r >> 2) + 4 * h; const bool vis = (row < kvalid) && (kpos0 + row < qpos); t = vis ? t : 0.f; }
;             wv[i] = t;
;         }
;         pw[2 * g] = pk2(wv[0], wv[1]); pw[2 * g + 1] = pk2(wv[2], wv[3]);
;     }
	v_exp_f32_e64 v147, -|v206|
	v_max_f32_e32 v149, 0, v206
	v_exp_f32_e64 v151, -|v205|
	v_max_f32_e32 v214, 0, v203
	v_add_f32_e32 v147, 1.0, v147
	v_log_f32_e32 v147, v147
	v_max_f32_e32 v215, 0, v202
	v_exp_f32_e64 v148, -|v207|
	v_max_f32_e32 v218, 0, v201
	v_add_f32_e32 v150, v149, v147
	v_exp_f32_e64 v147, -|v204|
	v_add_f32_e32 v149, 1.0, v151
	v_log_f32_e32 v208, v149
	v_exp_f32_e64 v149, -|v203|
	v_add_f32_e32 v147, 1.0, v147
	v_log_f32_e32 v212, v147
	v_exp_f32_e64 v147, -|v202|
	v_add_f32_e32 v149, 1.0, v149
	v_log_f32_e32 v216, v149
	v_exp_f32_e64 v149, -|v200|
	v_add_f32_e32 v147, 1.0, v147
	v_log_f32_e32 v217, v147
	v_exp_f32_e64 v147, -|v201|
	v_add_f32_e32 v148, 1.0, v148
	v_max_f32_e32 v219, 0, v200
	v_pk_add_f32 v[214:215], v[214:215], v[216:217]
	v_add_f32_e32 v147, 1.0, v147
	v_log_f32_e32 v216, v147
	v_add_f32_e32 v147, 1.0, v149
	v_log_f32_e32 v217, v147
	v_exp_f32_e64 v147, -|v199|
	v_exp_f32_e64 v149, -|v198|
	v_log_f32_e32 v148, v148
	v_pk_add_f32 v[216:217], v[218:219], v[216:217]
	v_add_f32_e32 v147, 1.0, v147
	v_log_f32_e32 v220, v147
	v_add_f32_e32 v147, 1.0, v149
	v_exp_f32_e64 v149, -|v197|
	v_log_f32_e32 v224, v147
	v_exp_f32_e64 v147, -|v196|
	v_max_f32_e32 v218, 0, v199
	v_add_f32_e32 v149, 1.0, v149
	v_log_f32_e32 v221, v149
	v_add_f32_e32 v147, 1.0, v147
	v_exp_f32_e64 v149, -|v195|
	v_log_f32_e32 v225, v147
	v_exp_f32_e64 v147, -|v194|
	v_max_f32_e32 v222, 0, v198
	v_add_f32_e32 v149, 1.0, v149
	v_log_f32_e32 v228, v149
	v_add_f32_e32 v147, 1.0, v147
	v_exp_f32_e64 v149, -|v193|
	v_log_f32_e32 v232, v147
	v_exp_f32_e64 v147, -|v192|
	v_max_f32_e32 v219, 0, v197
	v_add_f32_e32 v149, 1.0, v149
	v_log_f32_e32 v229, v149
	v_add_f32_e32 v147, 1.0, v147
	v_log_f32_e32 v233, v147
	v_max_f32_e32 v223, 0, v196
	v_max_f32_e32 v226, 0, v195
	v_max_f32_e32 v230, 0, v194
	v_max_f32_e32 v227, 0, v193
	v_max_f32_e32 v231, 0, v192
	v_pk_add_f32 v[218:219], v[218:219], v[220:221]
	v_pk_add_f32 v[220:221], v[222:223], v[224:225]
	v_pk_add_f32 v[224:225], v[226:227], v[228:229]
	v_pk_add_f32 v[226:227], v[230:231], v[232:233]
	v_pk_add_f32 v[234:235], v[214:215], v[214:215] op_sel_hi:[0,1]
	v_pk_add_f32 v[236:237], v[216:217], v[216:217] op_sel_hi:[0,1]
	v_pk_add_f32 v[222:223], v[218:219], v[220:221]
	v_pk_add_f32 v[228:229], v[224:225], v[226:227]
	v_max_f32_e32 v146, 0, v207
	v_pk_add_f32 v[222:223], v[222:223], v[222:223] op_sel:[0,1] op_sel_hi:[1,0]
	v_pk_add_f32 v[228:229], v[228:229], v[228:229] op_sel:[0,1] op_sel_hi:[1,0]
	v_mov_b32_e32 v147, v235
	v_mov_b32_e32 v149, v237
	ds_bpermute_b32 v209, v184, v222
	ds_bpermute_b32 v213, v184, v228
	v_pk_add_f32 v[146:147], v[146:147], v[148:149]
	ds_bpermute_b32 v151, v184, v147
	v_max_f32_e32 v152, 0, v205
	v_max_f32_e32 v210, 0, v204
	v_mov_b32_e32 v211, v228
	v_mov_b32_e32 v153, v222
	s_waitcnt lgkmcnt(1)
	v_pk_add_f32 v[210:211], v[210:211], v[212:213]
	v_pk_add_f32 v[148:149], v[152:153], v[208:209]
	s_waitcnt lgkmcnt(0)
	v_pk_add_f32 v[222:223], v[146:147], v[150:151]
	v_pk_add_f32 v[152:153], v[148:149], v[210:211]
	v_cndmask_b32_e64 v151, 0, v151, s[36:37]
	v_pk_add_f32 v[222:223], v[222:223], v[152:153]
	ds_bpermute_b32 v208, v184, v222
	v_add_f32_e32 v147, v189, v223
	s_mov_b64 s[10:11], 0
	s_waitcnt lgkmcnt(0)
	v_cndmask_b32_e64 v149, 0, v208, s[36:37]
	v_add_f32_e32 v147, v149, v147
	v_add_f32_e32 v147, v210, v147
	v_fma_f32 v149, v69, s16, -v147
	v_add_f32_e32 v147, v148, v147
	v_fma_f32 v148, v68, s16, -v147
	v_add_f32_e32 v147, v150, v147
	v_fma_f32 v150, v67, s16, -v147
	v_add_f32_e32 v146, v146, v147
	v_add_f32_e32 v147, v189, v153
	v_add_f32_e32 v147, v151, v147
	v_add_f32_e32 v147, v217, v147
	v_fma_f32 v151, v73, s16, -v147
	v_add_f32_e32 v147, v216, v147
	v_fma_f32 v146, v66, s16, -v146
	v_fma_f32 v152, v72, s16, -v147
	v_exp_f32_e32 v149, v149
	v_exp_f32_e32 v148, v148
	v_exp_f32_e32 v150, v150
	v_exp_f32_e32 v146, v146
	v_exp_f32_e32 v151, v151
	v_add_f32_e32 v147, v215, v147
	v_exp_f32_e32 v152, v152
	v_fma_f32 v153, v71, s16, -v147
	v_add_f32_e32 v147, v214, v147
	v_fma_f32 v147, v70, s16, -v147
	v_exp_f32_e32 v153, v153
	v_exp_f32_e32 v210, v147
	v_cvt_pk_bf16_f32 v146, v146, v150
	v_cvt_pk_bf16_f32 v147, v148, v149
	v_cvt_pk_bf16_f32 v149, v152, v151
	v_add_f32_e32 v150, v189, v211
	v_cndmask_b32_e64 v151, 0, v209, s[36:37]
	v_cndmask_b32_e64 v209, 0, v213, s[36:37]
	v_add_f32_e32 v150, v151, v150
	v_add_f32_e32 v209, v191, v209
	v_add_f32_e32 v150, v221, v150
	v_add_f32_e32 v209, v227, v209
	v_cvt_pk_bf16_f32 v148, v210, v153
	v_fma_f32 v151, v77, s16, -v150
	v_add_f32_e32 v150, v219, v150
	v_fma_f32 v210, v81, s16, -v209
	v_add_f32_e32 v209, v225, v209
	v_fma_f32 v152, v76, s16, -v150
	v_add_f32_e32 v150, v220, v150
	v_fma_f32 v211, v80, s16, -v209
	v_add_f32_e32 v209, v226, v209
	v_fma_f32 v153, v75, s16, -v150
	v_add_f32_e32 v150, v218, v150
	v_fma_f32 v212, v79, s16, -v209
	v_add_f32_e32 v209, v224, v209
	v_fma_f32 v150, v74, s16, -v150
	v_fma_f32 v209, v78, s16, -v209
	v_exp_f32_e32 v151, v151
	v_exp_f32_e32 v152, v152
	v_exp_f32_e32 v153, v153
	v_exp_f32_e32 v150, v150
	v_exp_f32_e32 v210, v210
	v_exp_f32_e32 v212, v212
	v_exp_f32_e32 v209, v209
	v_exp_f32_e32 v211, v211
	v_add_f32_e32 v208, v222, v208
	v_cvt_pk_bf16_f32 v150, v150, v153
	v_cvt_pk_bf16_f32 v151, v152, v151
	v_cvt_pk_bf16_f32 v152, v209, v212
	v_cvt_pk_bf16_f32 v153, v211, v210
	v_add_f32_e32 v208, v208, v223
